# DA loop: MFMA/VALU interleave - softmax of second key half (exp/sum/cvt/permlane) placed in the gaps of the first 16 PV MFMAs; V fragments double-buffered in dead K-fragment registers
# baseline (speedup 1.0000x reference)
; #define SBAR() __builtin_amdgcn_sched_barrier(0)
; template <int OFF> __device__ __forceinline__ s16x4 tr_read(int vb) { s16x4 r; asm volatile("ds_read_b64_tr_b16 %0, %1 offset:%2" : "=&v"(r) : "v"(vb), "i"(OFF) : "memory"); return r; }
; __device__ __forceinline__ void finishSM(f32x16& p0, f32x16& p1, float alpha, float& l_reg, bf16x8& pa0, bf16x8& pa1, bf16x8& pa2, bf16x8& pa3) {
; #pragma unroll
;   for (int r = 0; r < 16; ++r) p1[r] = __builtin_amdgcn_exp2f(p1[r]);
;   float ps = 0;
; #pragma unroll
;   for (int r = 0; r < 16; ++r) ps += p0[r];
; #pragma unroll
;   for (int r = 0; r < 16; ++r) ps += p1[r];
;   { auto rr = __builtin_amdgcn_permlane32_swap(__float_as_uint(ps), __float_as_uint(ps), false, false);
;     ps = __uint_as_float(rr[0]) + __uint_as_float(rr[1]); }
;   l_reg = l_reg * alpha + ps;
;   PK4(p0, 0, pa0); PK4(p0, 8, pa1); PK4(p1, 0, pa2); PK4(p1, 8, pa3);
; }
; template <int D0> __device__ __forceinline__ void pv_one_lean(f32x16& od, int vb, bf16x8 pa0, bf16x8 pa1, bf16x8 pa2, bf16x8 pa3) {
;     ...
;   { const s16x4 l0 = tr_read<v_rd_off(D0, 0, 0)>(vb), h0 = tr_read<v_rd_off(D0, 0, 1)>(vb), l1 = tr_read<v_rd_off(D0, 1, 0)>(vb), h1 = tr_read<v_rd_off(D0, 1, 1)>(vb);
;     asm volatile("s_waitcnt lgkmcnt(0)" ::: "memory"); SBAR();
;     od = __builtin_amdgcn_mfma_f32_32x32x16_bf16(pa0, PKL(l0, h0), od, 0, 0, 0); od = __builtin_amdgcn_mfma_f32_32x32x16_bf16(pa1, PKL(l1, h1), od, 0, 0, 0); }
;   SBAR();
;   { const s16x4 l2 = tr_read<v_rd_off(D0, 2, 0)>(vb), h2 = tr_read<v_rd_off(D0, 2, 1)>(vb), l3 = tr_read<v_rd_off(D0, 3, 0)>(vb), h3 = tr_read<v_rd_off(D0, 3, 1)>(vb);
;     asm volatile("s_waitcnt lgkmcnt(0)" ::: "memory"); SBAR();
;     od = __builtin_amdgcn_mfma_f32_32x32x16_bf16(pa2, PKL(l2, h2), od, 0, 0, 0); od = __builtin_amdgcn_mfma_f32_32x32x16_bf16(pa3, PKL(l3, h3), od, 0, 0, 0); }
;     ...
; }
; __device__ __forceinline__ void pv_d0_lean(f32x16* o, int vb, bf16x8 pa0, bf16x8 pa1, bf16x8 pa2, bf16x8 pa3) {
;   pv_one_lean<0>(o[0], vb, pa0, pa1, pa2, pa3); SBAR(); pv_one_lean<1>(o[1], vb, pa0, pa1, pa2, pa3); SBAR(); pv_one_lean<2>(o[2], vb, pa0, pa1, pa2, pa3); SBAR(); pv_one_lean<3>(o[3], vb, pa0, pa1, pa2, pa3);
; }
.LBB0_1936:
	v_cndmask_b32_e64 v238, v241, v238, s[4:5]
	v_sub_f32_e32 v0, v0, v238
	v_mul_f32_e32 v0, 0x3e0293ee, v0
	v_fmamk_f32 v146, v146, 0x3e0293ee, v0
	v_fmamk_f32 v147, v147, 0x3e0293ee, v0
	v_fmamk_f32 v148, v148, 0x3e0293ee, v0
	v_fmamk_f32 v149, v149, 0x3e0293ee, v0
	v_fmamk_f32 v150, v150, 0x3e0293ee, v0
	v_fmamk_f32 v151, v151, 0x3e0293ee, v0
	v_fmamk_f32 v152, v152, 0x3e0293ee, v0
	v_fmamk_f32 v153, v153, 0x3e0293ee, v0
	v_fmamk_f32 v154, v154, 0x3e0293ee, v0
	v_fmamk_f32 v155, v155, 0x3e0293ee, v0
	v_fmamk_f32 v156, v156, 0x3e0293ee, v0
	v_fmamk_f32 v157, v157, 0x3e0293ee, v0
	v_fmamk_f32 v158, v158, 0x3e0293ee, v0
	v_fmamk_f32 v159, v159, 0x3e0293ee, v0
	v_fmamk_f32 v160, v160, 0x3e0293ee, v0
	v_fmamk_f32 v161, v161, 0x3e0293ee, v0
	v_fmamk_f32 v162, v162, 0x3e0293ee, v0
	v_fmamk_f32 v163, v163, 0x3e0293ee, v0
	v_fmamk_f32 v164, v164, 0x3e0293ee, v0
	v_fmamk_f32 v165, v165, 0x3e0293ee, v0
	v_fmamk_f32 v166, v166, 0x3e0293ee, v0
	v_fmamk_f32 v167, v167, 0x3e0293ee, v0
	v_fmamk_f32 v168, v168, 0x3e0293ee, v0
	v_fmamk_f32 v169, v169, 0x3e0293ee, v0
	v_fmamk_f32 v170, v170, 0x3e0293ee, v0
	v_fmamk_f32 v171, v171, 0x3e0293ee, v0
	v_fmamk_f32 v172, v172, 0x3e0293ee, v0
	v_fmamk_f32 v173, v173, 0x3e0293ee, v0
	v_fmamk_f32 v174, v174, 0x3e0293ee, v0
	v_fmamk_f32 v175, v175, 0x3e0293ee, v0
	v_fmamk_f32 v176, v176, 0x3e0293ee, v0
	v_fmac_f32_e32 v0, 0x3e0293ee, v177
	v_exp_f32_e32 v146, v146
	v_exp_f32_e32 v147, v147
	v_exp_f32_e32 v148, v148
	v_add_f32_e32 v177, 0, v146
	v_exp_f32_e32 v149, v149
	v_add_f32_e32 v177, v147, v177
	v_exp_f32_e32 v150, v150
	v_add_f32_e32 v177, v148, v177
	v_exp_f32_e32 v151, v151
	v_add_f32_e32 v177, v149, v177
	v_exp_f32_e32 v152, v152
	v_add_f32_e32 v177, v150, v177
	v_exp_f32_e32 v153, v153
	v_add_f32_e32 v177, v151, v177
	v_exp_f32_e32 v154, v154
	v_add_f32_e32 v177, v152, v177
	v_exp_f32_e32 v155, v155
	v_add_f32_e32 v177, v153, v177
	v_exp_f32_e32 v156, v156
	v_add_f32_e32 v177, v154, v177
	v_exp_f32_e32 v157, v157
	v_add_f32_e32 v177, v155, v177
	v_exp_f32_e32 v158, v158
	v_add_f32_e32 v177, v156, v177
	v_exp_f32_e32 v159, v159
	v_add_f32_e32 v177, v157, v177
	v_exp_f32_e32 v160, v160
	v_add_f32_e32 v177, v158, v177
	v_exp_f32_e32 v161, v161
	v_add_f32_e32 v177, v159, v177
	v_add_f32_e32 v177, v160, v177
	v_add_f32_e32 v177, v161, v177
	v_cvt_pk_bf16_f32 v146, v146, v147
	v_cvt_pk_bf16_f32 v147, v148, v149
	v_cvt_pk_bf16_f32 v148, v150, v151
	v_cvt_pk_bf16_f32 v149, v152, v153
	v_cvt_pk_bf16_f32 v150, v154, v155
	v_cvt_pk_bf16_f32 v151, v156, v157
	v_cvt_pk_bf16_f32 v152, v158, v159
	v_cvt_pk_bf16_f32 v153, v160, v161
	v_permlane32_swap_b32_e32 v146, v148
	v_permlane32_swap_b32_e32 v147, v149
	v_permlane32_swap_b32_e32 v150, v152
	v_permlane32_swap_b32_e32 v151, v153
	s_setprio 1
	v_lshl_add_u32 v154, s40, 15, v237
	ds_read_b64_tr_b16 v[210:211], v154 offset:0
	ds_read_b64_tr_b16 v[212:213], v154 offset:0x800
	ds_read_b64_tr_b16 v[214:215], v154 offset:0x1000
	ds_read_b64_tr_b16 v[216:217], v154 offset:0x1800
	ds_read_b64_tr_b16 v[218:219], v154 offset:0x200
	ds_read_b64_tr_b16 v[220:221], v154 offset:0xa00
	ds_read_b64_tr_b16 v[222:223], v154 offset:0x1200
	ds_read_b64_tr_b16 v[224:225], v154 offset:0x1a00
	s_waitcnt lgkmcnt(4)
	v_mfma_f32_32x32x16_bf16 v[114:129], v[146:149], v[210:213], v[114:129]
	v_exp_f32_e32 v162, v162
	v_exp_f32_e32 v163, v163
	v_mfma_f32_32x32x16_bf16 v[114:129], v[150:153], v[214:217], v[114:129]
	v_exp_f32_e32 v164, v164
	v_exp_f32_e32 v165, v165
	ds_read_b64_tr_b16 v[210:211], v154 offset:0x400
	ds_read_b64_tr_b16 v[212:213], v154 offset:0xc00
	ds_read_b64_tr_b16 v[214:215], v154 offset:0x1400
	ds_read_b64_tr_b16 v[216:217], v154 offset:0x1c00
	s_waitcnt lgkmcnt(4)
	v_mfma_f32_32x32x16_bf16 v[98:113], v[146:149], v[218:221], v[98:113]
	v_exp_f32_e32 v166, v166
	v_exp_f32_e32 v167, v167
	v_add_f32_e32 v177, v162, v177
	v_add_f32_e32 v177, v163, v177
	v_mfma_f32_32x32x16_bf16 v[98:113], v[150:153], v[222:225], v[98:113]
	v_exp_f32_e32 v168, v168
	v_exp_f32_e32 v169, v169
	v_add_f32_e32 v177, v164, v177
	v_add_f32_e32 v177, v165, v177
	ds_read_b64_tr_b16 v[218:219], v154 offset:0x600
	ds_read_b64_tr_b16 v[220:221], v154 offset:0xe00
	ds_read_b64_tr_b16 v[222:223], v154 offset:0x1600
	ds_read_b64_tr_b16 v[224:225], v154 offset:0x1e00
	s_waitcnt lgkmcnt(4)
	v_mfma_f32_32x32x16_bf16 v[82:97], v[146:149], v[210:213], v[82:97]
	v_exp_f32_e32 v170, v170
	v_exp_f32_e32 v171, v171
	v_add_f32_e32 v177, v166, v177
	v_add_f32_e32 v177, v167, v177
	v_mfma_f32_32x32x16_bf16 v[82:97], v[150:153], v[214:217], v[82:97]
	v_exp_f32_e32 v172, v172
	v_exp_f32_e32 v173, v173
	v_add_f32_e32 v177, v168, v177
	v_add_f32_e32 v177, v169, v177
	v_add_u32_e32 v154, 0x4000, v154
	ds_read_b64_tr_b16 v[210:211], v154 offset:0
	ds_read_b64_tr_b16 v[212:213], v154 offset:0x800
	ds_read_b64_tr_b16 v[214:215], v154 offset:0x1000
	ds_read_b64_tr_b16 v[216:217], v154 offset:0x1800
	s_waitcnt lgkmcnt(4)
; #define SBAR() __builtin_amdgcn_sched_barrier(0)
; template <int OFF> __device__ __forceinline__ s16x4 tr_read(int vb) { s16x4 r; asm volatile("ds_read_b64_tr_b16 %0, %1 offset:%2" : "=&v"(r) : "v"(vb), "i"(OFF) : "memory"); return r; }
; __device__ __forceinline__ void finishSM(f32x16& p0, f32x16& p1, float alpha, float& l_reg, bf16x8& pa0, bf16x8& pa1, bf16x8& pa2, bf16x8& pa3) {
; #pragma unroll
;   for (int r = 0; r < 16; ++r) p1[r] = __builtin_amdgcn_exp2f(p1[r]);
;   float ps = 0;
; #pragma unroll
;   for (int r = 0; r < 16; ++r) ps += p0[r];
; #pragma unroll
;   for (int r = 0; r < 16; ++r) ps += p1[r];
;   { auto rr = __builtin_amdgcn_permlane32_swap(__float_as_uint(ps), __float_as_uint(ps), false, false);
;     ps = __uint_as_float(rr[0]) + __uint_as_float(rr[1]); }
;   l_reg = l_reg * alpha + ps;
;   PK4(p0, 0, pa0); PK4(p0, 8, pa1); PK4(p1, 0, pa2); PK4(p1, 8, pa3);
; }
; template <int D0> __device__ __forceinline__ void pv_one_lean(f32x16& od, int vb, bf16x8 pa0, bf16x8 pa1, bf16x8 pa2, bf16x8 pa3) {
;     ...
;   { const s16x4 l0 = tr_read<v_rd_off(D0, 0, 0)>(vb), h0 = tr_read<v_rd_off(D0, 0, 1)>(vb), l1 = tr_read<v_rd_off(D0, 1, 0)>(vb), h1 = tr_read<v_rd_off(D0, 1, 1)>(vb);
;     asm volatile("s_waitcnt lgkmcnt(0)" ::: "memory"); SBAR();
;     od = __builtin_amdgcn_mfma_f32_32x32x16_bf16(pa0, PKL(l0, h0), od, 0, 0, 0); od = __builtin_amdgcn_mfma_f32_32x32x16_bf16(pa1, PKL(l1, h1), od, 0, 0, 0); }
;   SBAR();
;   { const s16x4 l2 = tr_read<v_rd_off(D0, 2, 0)>(vb), h2 = tr_read<v_rd_off(D0, 2, 1)>(vb), l3 = tr_read<v_rd_off(D0, 3, 0)>(vb), h3 = tr_read<v_rd_off(D0, 3, 1)>(vb);
;     asm volatile("s_waitcnt lgkmcnt(0)" ::: "memory"); SBAR();
;     od = __builtin_amdgcn_mfma_f32_32x32x16_bf16(pa2, PKL(l2, h2), od, 0, 0, 0); od = __builtin_amdgcn_mfma_f32_32x32x16_bf16(pa3, PKL(l3, h3), od, 0, 0, 0); }
;     ...
; }
; __device__ __forceinline__ void pv_d0_lean(f32x16* o, int vb, bf16x8 pa0, bf16x8 pa1, bf16x8 pa2, bf16x8 pa3) {
;   pv_one_lean<0>(o[0], vb, pa0, pa1, pa2, pa3); SBAR(); pv_one_lean<1>(o[1], vb, pa0, pa1, pa2, pa3); SBAR(); pv_one_lean<2>(o[2], vb, pa0, pa1, pa2, pa3); SBAR(); pv_one_lean<3>(o[3], vb, pa0, pa1, pa2, pa3);
; }
	v_mfma_f32_32x32x16_bf16 v[66:81], v[146:149], v[218:221], v[66:81]
	v_exp_f32_e32 v174, v174
	v_exp_f32_e32 v175, v175
	v_add_f32_e32 v177, v170, v177
	v_add_f32_e32 v177, v171, v177
	v_mfma_f32_32x32x16_bf16 v[66:81], v[150:153], v[222:225], v[66:81]
	v_exp_f32_e32 v176, v176
	v_exp_f32_e32 v0, v0
	v_add_f32_e32 v177, v172, v177
	v_add_f32_e32 v177, v173, v177
	ds_read_b64_tr_b16 v[218:219], v154 offset:0x200
	ds_read_b64_tr_b16 v[220:221], v154 offset:0xa00
	ds_read_b64_tr_b16 v[222:223], v154 offset:0x1200
	ds_read_b64_tr_b16 v[224:225], v154 offset:0x1a00
	s_waitcnt lgkmcnt(4)
	v_mfma_f32_32x32x16_bf16 v[50:65], v[146:149], v[210:213], v[50:65]
	v_add_f32_e32 v177, v174, v177
	v_add_f32_e32 v177, v175, v177
	v_mfma_f32_32x32x16_bf16 v[50:65], v[150:153], v[214:217], v[50:65]
	v_add_f32_e32 v177, v176, v177
	v_add_f32_e32 v177, v0, v177
	ds_read_b64_tr_b16 v[210:211], v154 offset:0x400
	ds_read_b64_tr_b16 v[212:213], v154 offset:0xc00
	ds_read_b64_tr_b16 v[214:215], v154 offset:0x1400
	ds_read_b64_tr_b16 v[216:217], v154 offset:0x1c00
	s_waitcnt lgkmcnt(4)
	v_mfma_f32_32x32x16_bf16 v[34:49], v[146:149], v[218:221], v[34:49]
	v_mov_b32_e32 v156, v177
	v_mfma_f32_32x32x16_bf16 v[34:49], v[150:153], v[222:225], v[34:49]
	s_nop 0
	v_permlane32_swap_b32_e32 v177, v156
	v_add_f32_e32 v177, v177, v156
	ds_read_b64_tr_b16 v[218:219], v154 offset:0x600
	ds_read_b64_tr_b16 v[220:221], v154 offset:0xe00
	ds_read_b64_tr_b16 v[222:223], v154 offset:0x1600
	ds_read_b64_tr_b16 v[224:225], v154 offset:0x1e00
	s_waitcnt lgkmcnt(4)
	v_mfma_f32_32x32x16_bf16 v[18:33], v[146:149], v[210:213], v[18:33]
	v_cvt_pk_bf16_f32 v154, v162, v163
	v_cvt_pk_bf16_f32 v155, v164, v165
	v_cvt_pk_bf16_f32 v156, v166, v167
	v_cvt_pk_bf16_f32 v157, v168, v169
	v_mfma_f32_32x32x16_bf16 v[18:33], v[150:153], v[214:217], v[18:33]
	v_cvt_pk_bf16_f32 v158, v170, v171
	v_cvt_pk_bf16_f32 v159, v172, v173
	v_cvt_pk_bf16_f32 v160, v174, v175
	v_cvt_pk_bf16_f32 v161, v176, v0
	v_lshl_add_u32 v0, s40, 15, v237
	ds_read_b64_tr_b16 v[210:211], v0 offset:0x2000
	ds_read_b64_tr_b16 v[212:213], v0 offset:0x2800
	ds_read_b64_tr_b16 v[214:215], v0 offset:0x3000
	ds_read_b64_tr_b16 v[216:217], v0 offset:0x3800
	s_waitcnt lgkmcnt(4)
	v_mfma_f32_32x32x16_bf16 v[2:17], v[146:149], v[218:221], v[2:17]
	v_fmac_f32_e32 v177, v240, v229
	v_permlane32_swap_b32_e32 v154, v156
	v_permlane32_swap_b32_e32 v155, v157
	v_mfma_f32_32x32x16_bf16 v[2:17], v[150:153], v[222:225], v[2:17]
	v_permlane32_swap_b32_e32 v158, v160
	v_permlane32_swap_b32_e32 v159, v161
	v_mov_b32_e32 v240, v177
	ds_read_b64_tr_b16 v[218:219], v0 offset:0x2200
	ds_read_b64_tr_b16 v[220:221], v0 offset:0x2a00
	ds_read_b64_tr_b16 v[222:223], v0 offset:0x3200
	ds_read_b64_tr_b16 v[224:225], v0 offset:0x3a00
	s_waitcnt lgkmcnt(4)
	v_mfma_f32_32x32x16_bf16 v[114:129], v[154:157], v[210:213], v[114:129]
	v_mfma_f32_32x32x16_bf16 v[114:129], v[158:161], v[214:217], v[114:129]
	ds_read_b64_tr_b16 v[210:211], v0 offset:0x2400
	ds_read_b64_tr_b16 v[212:213], v0 offset:0x2c00
	ds_read_b64_tr_b16 v[214:215], v0 offset:0x3400
	ds_read_b64_tr_b16 v[216:217], v0 offset:0x3c00
	s_waitcnt lgkmcnt(4)
	v_mfma_f32_32x32x16_bf16 v[98:113], v[154:157], v[218:221], v[98:113]
	v_mfma_f32_32x32x16_bf16 v[98:113], v[158:161], v[222:225], v[98:113]
	ds_read_b64_tr_b16 v[218:219], v0 offset:0x2600
	ds_read_b64_tr_b16 v[220:221], v0 offset:0x2e00
	ds_read_b64_tr_b16 v[222:223], v0 offset:0x3600
	ds_read_b64_tr_b16 v[224:225], v0 offset:0x3e00
	s_waitcnt lgkmcnt(4)
	v_mfma_f32_32x32x16_bf16 v[82:97], v[154:157], v[210:213], v[82:97]
	v_mfma_f32_32x32x16_bf16 v[82:97], v[158:161], v[214:217], v[82:97]
	v_add_u32_e32 v0, 0x4000, v0
	ds_read_b64_tr_b16 v[210:211], v0 offset:0x2000
	ds_read_b64_tr_b16 v[212:213], v0 offset:0x2800
	ds_read_b64_tr_b16 v[214:215], v0 offset:0x3000
	ds_read_b64_tr_b16 v[216:217], v0 offset:0x3800
	s_waitcnt lgkmcnt(4)
	v_mfma_f32_32x32x16_bf16 v[66:81], v[154:157], v[218:221], v[66:81]
	v_mfma_f32_32x32x16_bf16 v[66:81], v[158:161], v[222:225], v[66:81]
	ds_read_b64_tr_b16 v[218:219], v0 offset:0x2200
	ds_read_b64_tr_b16 v[220:221], v0 offset:0x2a00
	ds_read_b64_tr_b16 v[222:223], v0 offset:0x3200
	ds_read_b64_tr_b16 v[224:225], v0 offset:0x3a00
	s_waitcnt lgkmcnt(4)
	v_mfma_f32_32x32x16_bf16 v[50:65], v[154:157], v[210:213], v[50:65]
	v_mfma_f32_32x32x16_bf16 v[50:65], v[158:161], v[214:217], v[50:65]
	ds_read_b64_tr_b16 v[210:211], v0 offset:0x2400
	ds_read_b64_tr_b16 v[212:213], v0 offset:0x2c00
	ds_read_b64_tr_b16 v[214:215], v0 offset:0x3400
	ds_read_b64_tr_b16 v[216:217], v0 offset:0x3c00
	s_waitcnt lgkmcnt(4)
	v_mfma_f32_32x32x16_bf16 v[34:49], v[154:157], v[218:221], v[34:49]
	v_mfma_f32_32x32x16_bf16 v[34:49], v[158:161], v[222:225], v[34:49]
	ds_read_b64_tr_b16 v[218:219], v0 offset:0x2600
	ds_read_b64_tr_b16 v[220:221], v0 offset:0x2e00
	ds_read_b64_tr_b16 v[222:223], v0 offset:0x3600
	ds_read_b64_tr_b16 v[224:225], v0 offset:0x3e00
	s_waitcnt lgkmcnt(4)
	v_mfma_f32_32x32x16_bf16 v[18:33], v[154:157], v[210:213], v[18:33]
	v_mfma_f32_32x32x16_bf16 v[18:33], v[158:161], v[214:217], v[18:33]
	s_waitcnt lgkmcnt(0)
	v_mfma_f32_32x32x16_bf16 v[2:17], v[154:157], v[218:221], v[2:17]
	v_mfma_f32_32x32x16_bf16 v[2:17], v[158:161], v[222:225], v[2:17]
	s_setprio 0
